# EpiResid epilogue: cross-lane sum-of-squares reduction through v_permlane32_swap + v_permlane16_swap instead of two ds_bpermute round trips
# speedup vs baseline: 1.0108x; 1.0108x over previous
; __device__ __forceinline__ float bf_lo(unsigned u) { return __uint_as_float(u << 16); }
; __device__ __forceinline__ float bf_hi(unsigned u) { return __uint_as_float(u & 0xffff0000u); }
; __device__ __forceinline__ unsigned pk_bf16(float lo, float hi) { const f32x2 v = {lo, hi}; const bf16x2_t b = __builtin_convertvector(v, bf16x2_t); return __builtin_bit_cast(unsigned, b); }
;     __device__ __forceinline__ void operator()(const f32x4 (&acc)[2][2][4][2], const pg8::Unit& u, int wr, int wc, int fr, int fq) const {
;     ...
;         const int row0 = u.pm * 256 + wr * 64 + fr, col0 = u.pn * 256 + wc * 32 + 4 * fq;
;         const bool rf32 = (rp != nullptr) && (u.pm < MP / 256);
; #pragma unroll
;         for (int ai = 0; ai < 2; ++ai)
; #pragma unroll
;             for (int m = 0; m < 4; ++m) {
;                 const int row = row0 + ai * 128 + m * 16; const size_t off = (size_t)row * DM + col0; float q = 0.f;
;                 f32x4 r4[2][2];
;                 if (rf32) {
; #pragma unroll
;                     for (int bj = 0; bj < 2; ++bj)
; #pragma unroll
;                         for (int n = 0; n < 2; ++n) r4[bj][n] = *(const f32x4*)(rp + off + bj * 128 + n * 16);
;                 } else {
; #pragma unroll
;                     for (int bj = 0; bj < 2; ++bj)
; #pragma unroll
;                         for (int n = 0; n < 2; ++n) { const u32x2 w = *(const u32x2*)(XB + off + bj * 128 + n * 16); r4[bj][n] = (f32x4){bf_lo(w.x), bf_hi(w.x), bf_lo(w.y), bf_hi(w.y)}; }
;                 }
; #pragma unroll
;                 for (int bj = 0; bj < 2; ++bj)
; #pragma unroll
;                     for (int n = 0; n < 2; ++n) { const f32x4 x4 = r4[bj][n] + acc[ai][bj][m][n];
;                         q += (x4[0] * x4[0] + x4[1] * x4[1]) + (x4[2] * x4[2] + x4[3] * x4[3]);
;                         u32x2 w; w.x = pk_bf16(x4[0], x4[1]); w.y = pk_bf16(x4[2], x4[3]); *(u32x2*)(XB + off + bj * 128 + n * 16) = w; }
;                 q += __shfl_xor(q, 16); q += __shfl_xor(q, 32);
;                 if (fq == 0) ssq[(size_t)row * 16 + u.pn * 4 + wc] = q;
.LBB0_1683:
	s_lshl_b32 s4, s51, 8
	v_mov_b32_e32 v158, v1
	s_add_i32 s4, s4, s46
	s_lshl_b32 s28, s50, 2
	v_add_u32_e32 v160, s4, v158
	v_ashrrev_i32_e32 v161, 31, v160
	v_lshl_or_b32 v158, s50, 8, v163
	v_lshlrev_b64 v[166:167], 11, v[160:161]
	v_ashrrev_i32_e32 v159, 31, v158
	v_lshl_add_u64 v[166:167], s[14:15], 0, v[166:167]
	v_lshl_add_u64 v[166:167], v[158:159], 1, v[166:167]
	s_ashr_i32 s29, s28, 31
	v_lshlrev_b32_e32 v252, 11, v160
	v_lshl_add_u32 v252, v158, 1, v252
	v_bfe_u32 v253, v190, 4, 1
	v_mul_u32_u24_e32 v253, 24, v253
	v_add_u32_e32 v252, v252, v253
	s_lshl_b32 s88, s45, 2
	v_lshl_add_u32 v189, v160, 6, s88
	v_lshl_add_u32 v189, s28, 2, v189
	global_load_dwordx4 v[204:207], v252, s[14:15]
	global_load_dwordx4 v[208:211], v252, s[14:15] offset:256
	v_add_u32_e32 v253, 0x8000, v252
	global_load_dwordx4 v[212:215], v253, s[14:15]
	global_load_dwordx4 v[216:219], v253, s[14:15] offset:256
	v_add_u32_e32 v253, 0x10000, v252
	global_load_dwordx4 v[220:223], v253, s[14:15]
	global_load_dwordx4 v[224:227], v253, s[14:15] offset:256
	v_add_u32_e32 v253, 0x18000, v252
	global_load_dwordx4 v[228:231], v253, s[14:15]
	global_load_dwordx4 v[232:235], v253, s[14:15] offset:256
	v_add_u32_e32 v253, 0x40000, v252
	global_load_dwordx4 v[236:239], v253, s[14:15]
	global_load_dwordx4 v[240:243], v253, s[14:15] offset:256
	v_add_u32_e32 v253, 0x48000, v252
	global_load_dwordx4 v[244:247], v253, s[14:15]
	global_load_dwordx4 v[248:251], v253, s[14:15] offset:256
	s_waitcnt vmcnt(10)
	v_permlane16_swap_b32_e32 v204, v206
	v_permlane16_swap_b32_e32 v205, v207
	v_permlane16_swap_b32_e32 v208, v210
	v_permlane16_swap_b32_e32 v209, v211
	v_lshlrev_b32_e32 v166, 16, v204
	v_and_b32_e32 v167, 0xffff0000, v204
	v_lshlrev_b32_e32 v168, 16, v205
	v_and_b32_e32 v169, 0xffff0000, v205
	v_lshlrev_b32_e32 v170, 16, v206
	v_and_b32_e32 v171, 0xffff0000, v206
	v_lshlrev_b32_e32 v172, 16, v207
	v_and_b32_e32 v173, 0xffff0000, v207
	v_lshlrev_b32_e32 v174, 16, v208
	v_and_b32_e32 v175, 0xffff0000, v208
	v_lshlrev_b32_e32 v176, 16, v209
	v_and_b32_e32 v177, 0xffff0000, v209
	v_lshlrev_b32_e32 v178, 16, v210
	v_and_b32_e32 v179, 0xffff0000, v210
	v_lshlrev_b32_e32 v180, 16, v211
	v_and_b32_e32 v181, 0xffff0000, v211
	v_pk_add_f32 v[126:127], v[126:127], v[166:167]
	v_pk_add_f32 v[128:129], v[128:129], v[168:169]
	v_pk_add_f32 v[122:123], v[122:123], v[170:171]
	v_pk_add_f32 v[124:125], v[124:125], v[172:173]
	v_pk_add_f32 v[118:119], v[118:119], v[174:175]
	v_pk_add_f32 v[120:121], v[120:121], v[176:177]
	v_pk_add_f32 v[114:115], v[114:115], v[178:179]
	v_pk_add_f32 v[116:117], v[116:117], v[180:181]
	v_add_u32_e32 v253, 0x50000, v252
	global_load_dwordx4 v[204:207], v253, s[14:15]
	global_load_dwordx4 v[208:211], v253, s[14:15] offset:256
	v_cvt_pk_bf16_f32 v166, v126, v127
	v_cvt_pk_bf16_f32 v167, v128, v129
	v_cvt_pk_bf16_f32 v168, v122, v123
	v_cvt_pk_bf16_f32 v169, v124, v125
	v_cvt_pk_bf16_f32 v170, v118, v119
	v_cvt_pk_bf16_f32 v171, v120, v121
	v_cvt_pk_bf16_f32 v172, v114, v115
	v_cvt_pk_bf16_f32 v173, v116, v117
	v_mul_f32_e32 v174, v126, v126
	v_mul_f32_e32 v175, v122, v122
	v_mul_f32_e32 v176, v118, v118
	v_mul_f32_e32 v177, v114, v114
	v_fmac_f32_e32 v174, v127, v127
	v_fmac_f32_e32 v175, v123, v123
	v_fmac_f32_e32 v176, v119, v119
	v_fmac_f32_e32 v177, v115, v115
	v_fmac_f32_e32 v174, v128, v128
	v_fmac_f32_e32 v175, v124, v124
	v_fmac_f32_e32 v176, v120, v120
	v_fmac_f32_e32 v177, v116, v116
	v_fmac_f32_e32 v174, v129, v129
	v_fmac_f32_e32 v175, v125, v125
	v_fmac_f32_e32 v176, v121, v121
	v_fmac_f32_e32 v177, v117, v117
	v_add_f32_e32 v174, v174, v175
	v_add_f32_e32 v176, v176, v177
	v_add_f32_e32 v178, v174, v176
	v_mov_b32_e32 v179, v178
	v_permlane16_swap_b32_e32 v166, v168
	v_permlane16_swap_b32_e32 v167, v169
	v_permlane32_swap_b32_e32 v179, v178
	v_permlane16_swap_b32_e32 v170, v172
	v_permlane16_swap_b32_e32 v171, v173
	global_store_dwordx4 v252, v[166:169], s[14:15]
	global_store_dwordx4 v252, v[170:173], s[14:15] offset:256
	v_add_f32_e32 v178, v178, v179
	v_mov_b32_e32 v179, v178
	s_nop 0
	s_nop 0
	v_permlane16_swap_b32_e32 v179, v178
	v_add_f32_e32 v178, v178, v179
	s_and_saveexec_b64 s[30:31], s[8:9]
	global_store_dword v189, v178, s[16:17]
	s_or_b64 exec, exec, s[30:31]
	s_waitcnt vmcnt(12)
; __device__ __forceinline__ float bf_lo(unsigned u) { return __uint_as_float(u << 16); }
; __device__ __forceinline__ float bf_hi(unsigned u) { return __uint_as_float(u & 0xffff0000u); }
; __device__ __forceinline__ unsigned pk_bf16(float lo, float hi) { const f32x2 v = {lo, hi}; const bf16x2_t b = __builtin_convertvector(v, bf16x2_t); return __builtin_bit_cast(unsigned, b); }
;     __device__ __forceinline__ void operator()(const f32x4 (&acc)[2][2][4][2], const pg8::Unit& u, int wr, int wc, int fr, int fq) const {
;     ...
;                     for (int bj = 0; bj < 2; ++bj)
; #pragma unroll
;                         for (int n = 0; n < 2; ++n) { const u32x2 w = *(const u32x2*)(XB + off + bj * 128 + n * 16); r4[bj][n] = (f32x4){bf_lo(w.x), bf_hi(w.x), bf_lo(w.y), bf_hi(w.y)}; }
;                 }
; #pragma unroll
;                 for (int bj = 0; bj < 2; ++bj)
; #pragma unroll
;                     for (int n = 0; n < 2; ++n) { const f32x4 x4 = r4[bj][n] + acc[ai][bj][m][n];
;                         q += (x4[0] * x4[0] + x4[1] * x4[1]) + (x4[2] * x4[2] + x4[3] * x4[3]);
;                         u32x2 w; w.x = pk_bf16(x4[0], x4[1]); w.y = pk_bf16(x4[2], x4[3]); *(u32x2*)(XB + off + bj * 128 + n * 16) = w; }
;                 q += __shfl_xor(q, 16); q += __shfl_xor(q, 32);
;                 if (fq == 0) ssq[(size_t)row * 16 + u.pn * 4 + wc] = q;
	v_permlane16_swap_b32_e32 v212, v214
	v_permlane16_swap_b32_e32 v213, v215
	v_permlane16_swap_b32_e32 v216, v218
	v_permlane16_swap_b32_e32 v217, v219
	v_lshlrev_b32_e32 v166, 16, v212
	v_and_b32_e32 v167, 0xffff0000, v212
	v_lshlrev_b32_e32 v168, 16, v213
	v_and_b32_e32 v169, 0xffff0000, v213
	v_lshlrev_b32_e32 v170, 16, v214
	v_and_b32_e32 v171, 0xffff0000, v214
	v_lshlrev_b32_e32 v172, 16, v215
	v_and_b32_e32 v173, 0xffff0000, v215
	v_lshlrev_b32_e32 v174, 16, v216
	v_and_b32_e32 v175, 0xffff0000, v216
	v_lshlrev_b32_e32 v176, 16, v217
	v_and_b32_e32 v177, 0xffff0000, v217
	v_lshlrev_b32_e32 v178, 16, v218
	v_and_b32_e32 v179, 0xffff0000, v218
	v_lshlrev_b32_e32 v180, 16, v219
	v_and_b32_e32 v181, 0xffff0000, v219
	v_pk_add_f32 v[110:111], v[110:111], v[166:167]
	v_pk_add_f32 v[112:113], v[112:113], v[168:169]
	v_pk_add_f32 v[106:107], v[106:107], v[170:171]
	v_pk_add_f32 v[108:109], v[108:109], v[172:173]
	v_pk_add_f32 v[102:103], v[102:103], v[174:175]
	v_pk_add_f32 v[104:105], v[104:105], v[176:177]
	v_pk_add_f32 v[98:99], v[98:99], v[178:179]
	v_pk_add_f32 v[100:101], v[100:101], v[180:181]
	v_add_u32_e32 v253, 0x58000, v252
	global_load_dwordx4 v[212:215], v253, s[14:15]
	global_load_dwordx4 v[216:219], v253, s[14:15] offset:256
	v_cvt_pk_bf16_f32 v166, v110, v111
	v_cvt_pk_bf16_f32 v167, v112, v113
	v_cvt_pk_bf16_f32 v168, v106, v107
	v_cvt_pk_bf16_f32 v169, v108, v109
	v_cvt_pk_bf16_f32 v170, v102, v103
	v_cvt_pk_bf16_f32 v171, v104, v105
	v_cvt_pk_bf16_f32 v172, v98, v99
	v_cvt_pk_bf16_f32 v173, v100, v101
	v_mul_f32_e32 v174, v110, v110
	v_mul_f32_e32 v175, v106, v106
	v_mul_f32_e32 v176, v102, v102
	v_mul_f32_e32 v177, v98, v98
	v_fmac_f32_e32 v174, v111, v111
	v_fmac_f32_e32 v175, v107, v107
	v_fmac_f32_e32 v176, v103, v103
	v_fmac_f32_e32 v177, v99, v99
	v_fmac_f32_e32 v174, v112, v112
	v_fmac_f32_e32 v175, v108, v108
	v_fmac_f32_e32 v176, v104, v104
	v_fmac_f32_e32 v177, v100, v100
	v_fmac_f32_e32 v174, v113, v113
	v_fmac_f32_e32 v175, v109, v109
	v_fmac_f32_e32 v176, v105, v105
	v_fmac_f32_e32 v177, v101, v101
	v_add_f32_e32 v174, v174, v175
	v_add_f32_e32 v176, v176, v177
	v_add_f32_e32 v178, v174, v176
	v_mov_b32_e32 v179, v178
	v_permlane16_swap_b32_e32 v166, v168
	v_permlane16_swap_b32_e32 v167, v169
	v_permlane32_swap_b32_e32 v179, v178
	v_permlane16_swap_b32_e32 v170, v172
	v_permlane16_swap_b32_e32 v171, v173
	v_add_u32_e32 v253, 0x8000, v252
	global_store_dwordx4 v253, v[166:169], s[14:15]
	global_store_dwordx4 v253, v[170:173], s[14:15] offset:256
	v_add_f32_e32 v178, v178, v179
	v_mov_b32_e32 v179, v178
	s_nop 0
	s_nop 0
	v_permlane16_swap_b32_e32 v179, v178
	v_add_f32_e32 v178, v178, v179
	s_and_saveexec_b64 s[30:31], s[8:9]
	global_store_dword v189, v178, s[16:17] offset:1024
	s_or_b64 exec, exec, s[30:31]
	s_waitcnt vmcnt(14)
	v_permlane16_swap_b32_e32 v220, v222
	v_permlane16_swap_b32_e32 v221, v223
	v_permlane16_swap_b32_e32 v224, v226
	v_permlane16_swap_b32_e32 v225, v227
	v_lshlrev_b32_e32 v166, 16, v220
	v_and_b32_e32 v167, 0xffff0000, v220
	v_lshlrev_b32_e32 v168, 16, v221
	v_and_b32_e32 v169, 0xffff0000, v221
	v_lshlrev_b32_e32 v170, 16, v222
	v_and_b32_e32 v171, 0xffff0000, v222
	v_lshlrev_b32_e32 v172, 16, v223
	v_and_b32_e32 v173, 0xffff0000, v223
	v_lshlrev_b32_e32 v174, 16, v224
	v_and_b32_e32 v175, 0xffff0000, v224
	v_lshlrev_b32_e32 v176, 16, v225
	v_and_b32_e32 v177, 0xffff0000, v225
	v_lshlrev_b32_e32 v178, 16, v226
	v_and_b32_e32 v179, 0xffff0000, v226
	v_lshlrev_b32_e32 v180, 16, v227
	v_and_b32_e32 v181, 0xffff0000, v227
	v_pk_add_f32 v[94:95], v[94:95], v[166:167]
	v_pk_add_f32 v[96:97], v[96:97], v[168:169]
	v_pk_add_f32 v[90:91], v[90:91], v[170:171]
	v_pk_add_f32 v[92:93], v[92:93], v[172:173]
	v_pk_add_f32 v[86:87], v[86:87], v[174:175]
	v_pk_add_f32 v[88:89], v[88:89], v[176:177]
	v_pk_add_f32 v[82:83], v[82:83], v[178:179]
	v_pk_add_f32 v[84:85], v[84:85], v[180:181]
	v_cvt_pk_bf16_f32 v166, v94, v95
	v_cvt_pk_bf16_f32 v167, v96, v97
	v_cvt_pk_bf16_f32 v168, v90, v91
	v_cvt_pk_bf16_f32 v169, v92, v93
	v_cvt_pk_bf16_f32 v170, v86, v87
	v_cvt_pk_bf16_f32 v171, v88, v89
	v_cvt_pk_bf16_f32 v172, v82, v83
	v_cvt_pk_bf16_f32 v173, v84, v85
	v_mul_f32_e32 v174, v94, v94
	v_mul_f32_e32 v175, v90, v90
	v_mul_f32_e32 v176, v86, v86
	v_mul_f32_e32 v177, v82, v82
	v_fmac_f32_e32 v174, v95, v95
	v_fmac_f32_e32 v175, v91, v91
	v_fmac_f32_e32 v176, v87, v87
	v_fmac_f32_e32 v177, v83, v83
	v_fmac_f32_e32 v174, v96, v96
	v_fmac_f32_e32 v175, v92, v92
	v_fmac_f32_e32 v176, v88, v88
	v_fmac_f32_e32 v177, v84, v84
	v_fmac_f32_e32 v174, v97, v97
	v_fmac_f32_e32 v175, v93, v93
	v_fmac_f32_e32 v176, v89, v89
	v_fmac_f32_e32 v177, v85, v85
	v_add_f32_e32 v174, v174, v175
	v_add_f32_e32 v176, v176, v177
	v_add_f32_e32 v178, v174, v176
	v_mov_b32_e32 v179, v178
	v_permlane16_swap_b32_e32 v166, v168
	v_permlane16_swap_b32_e32 v167, v169
	v_permlane32_swap_b32_e32 v179, v178
	v_permlane16_swap_b32_e32 v170, v172
	v_permlane16_swap_b32_e32 v171, v173
	v_add_u32_e32 v253, 0x10000, v252
	global_store_dwordx4 v253, v[166:169], s[14:15]
	global_store_dwordx4 v253, v[170:173], s[14:15] offset:256
	v_add_f32_e32 v178, v178, v179
	v_mov_b32_e32 v179, v178
	s_nop 0
	s_nop 0
	v_permlane16_swap_b32_e32 v179, v178
	v_add_f32_e32 v178, v178, v179
	s_and_saveexec_b64 s[30:31], s[8:9]
	global_store_dword v189, v178, s[16:17] offset:2048
	s_or_b64 exec, exec, s[30:31]
	s_waitcnt vmcnt(14)
; __device__ __forceinline__ float bf_lo(unsigned u) { return __uint_as_float(u << 16); }
; __device__ __forceinline__ float bf_hi(unsigned u) { return __uint_as_float(u & 0xffff0000u); }
; __device__ __forceinline__ unsigned pk_bf16(float lo, float hi) { const f32x2 v = {lo, hi}; const bf16x2_t b = __builtin_convertvector(v, bf16x2_t); return __builtin_bit_cast(unsigned, b); }
;     __device__ __forceinline__ void operator()(const f32x4 (&acc)[2][2][4][2], const pg8::Unit& u, int wr, int wc, int fr, int fq) const {
;     ...
;                     for (int bj = 0; bj < 2; ++bj)
; #pragma unroll
;                         for (int n = 0; n < 2; ++n) { const u32x2 w = *(const u32x2*)(XB + off + bj * 128 + n * 16); r4[bj][n] = (f32x4){bf_lo(w.x), bf_hi(w.x), bf_lo(w.y), bf_hi(w.y)}; }
;                 }
; #pragma unroll
;                 for (int bj = 0; bj < 2; ++bj)
; #pragma unroll
;                     for (int n = 0; n < 2; ++n) { const f32x4 x4 = r4[bj][n] + acc[ai][bj][m][n];
;                         q += (x4[0] * x4[0] + x4[1] * x4[1]) + (x4[2] * x4[2] + x4[3] * x4[3]);
;                         u32x2 w; w.x = pk_bf16(x4[0], x4[1]); w.y = pk_bf16(x4[2], x4[3]); *(u32x2*)(XB + off + bj * 128 + n * 16) = w; }
;                 q += __shfl_xor(q, 16); q += __shfl_xor(q, 32);
;                 if (fq == 0) ssq[(size_t)row * 16 + u.pn * 4 + wc] = q;
	v_permlane16_swap_b32_e32 v228, v230
	v_permlane16_swap_b32_e32 v229, v231
	v_permlane16_swap_b32_e32 v232, v234
	v_permlane16_swap_b32_e32 v233, v235
	v_lshlrev_b32_e32 v166, 16, v228
	v_and_b32_e32 v167, 0xffff0000, v228
	v_lshlrev_b32_e32 v168, 16, v229
	v_and_b32_e32 v169, 0xffff0000, v229
	v_lshlrev_b32_e32 v170, 16, v230
	v_and_b32_e32 v171, 0xffff0000, v230
	v_lshlrev_b32_e32 v172, 16, v231
	v_and_b32_e32 v173, 0xffff0000, v231
	v_lshlrev_b32_e32 v174, 16, v232
	v_and_b32_e32 v175, 0xffff0000, v232
	v_lshlrev_b32_e32 v176, 16, v233
	v_and_b32_e32 v177, 0xffff0000, v233
	v_lshlrev_b32_e32 v178, 16, v234
	v_and_b32_e32 v179, 0xffff0000, v234
	v_lshlrev_b32_e32 v180, 16, v235
	v_and_b32_e32 v181, 0xffff0000, v235
	v_pk_add_f32 v[78:79], v[78:79], v[166:167]
	v_pk_add_f32 v[80:81], v[80:81], v[168:169]
	v_pk_add_f32 v[74:75], v[74:75], v[170:171]
	v_pk_add_f32 v[76:77], v[76:77], v[172:173]
	v_pk_add_f32 v[70:71], v[70:71], v[174:175]
	v_pk_add_f32 v[72:73], v[72:73], v[176:177]
	v_pk_add_f32 v[66:67], v[66:67], v[178:179]
	v_pk_add_f32 v[68:69], v[68:69], v[180:181]
	v_cvt_pk_bf16_f32 v166, v78, v79
	v_cvt_pk_bf16_f32 v167, v80, v81
	v_cvt_pk_bf16_f32 v168, v74, v75
	v_cvt_pk_bf16_f32 v169, v76, v77
	v_cvt_pk_bf16_f32 v170, v70, v71
	v_cvt_pk_bf16_f32 v171, v72, v73
	v_cvt_pk_bf16_f32 v172, v66, v67
	v_cvt_pk_bf16_f32 v173, v68, v69
	v_mul_f32_e32 v174, v78, v78
	v_mul_f32_e32 v175, v74, v74
	v_mul_f32_e32 v176, v70, v70
	v_mul_f32_e32 v177, v66, v66
	v_fmac_f32_e32 v174, v79, v79
	v_fmac_f32_e32 v175, v75, v75
	v_fmac_f32_e32 v176, v71, v71
	v_fmac_f32_e32 v177, v67, v67
	v_fmac_f32_e32 v174, v80, v80
	v_fmac_f32_e32 v175, v76, v76
	v_fmac_f32_e32 v176, v72, v72
	v_fmac_f32_e32 v177, v68, v68
	v_fmac_f32_e32 v174, v81, v81
	v_fmac_f32_e32 v175, v77, v77
	v_fmac_f32_e32 v176, v73, v73
	v_fmac_f32_e32 v177, v69, v69
	v_add_f32_e32 v174, v174, v175
	v_add_f32_e32 v176, v176, v177
	v_add_f32_e32 v178, v174, v176
	v_mov_b32_e32 v179, v178
	v_permlane16_swap_b32_e32 v166, v168
	v_permlane16_swap_b32_e32 v167, v169
	v_permlane32_swap_b32_e32 v179, v178
	v_permlane16_swap_b32_e32 v170, v172
	v_permlane16_swap_b32_e32 v171, v173
	v_add_u32_e32 v253, 0x18000, v252
	global_store_dwordx4 v253, v[166:169], s[14:15]
	global_store_dwordx4 v253, v[170:173], s[14:15] offset:256
	v_add_f32_e32 v178, v178, v179
	v_mov_b32_e32 v179, v178
	s_nop 0
	s_nop 0
	v_permlane16_swap_b32_e32 v179, v178
	v_add_f32_e32 v178, v178, v179
	s_and_saveexec_b64 s[30:31], s[8:9]
	global_store_dword v189, v178, s[16:17] offset:3072
	s_or_b64 exec, exec, s[30:31]
	s_waitcnt vmcnt(14)
	v_permlane16_swap_b32_e32 v236, v238
	v_permlane16_swap_b32_e32 v237, v239
	v_permlane16_swap_b32_e32 v240, v242
	v_permlane16_swap_b32_e32 v241, v243
	v_lshlrev_b32_e32 v166, 16, v236
	v_and_b32_e32 v167, 0xffff0000, v236
	v_lshlrev_b32_e32 v168, 16, v237
	v_and_b32_e32 v169, 0xffff0000, v237
	v_lshlrev_b32_e32 v170, 16, v238
	v_and_b32_e32 v171, 0xffff0000, v238
	v_lshlrev_b32_e32 v172, 16, v239
	v_and_b32_e32 v173, 0xffff0000, v239
	v_lshlrev_b32_e32 v174, 16, v240
	v_and_b32_e32 v175, 0xffff0000, v240
	v_lshlrev_b32_e32 v176, 16, v241
	v_and_b32_e32 v177, 0xffff0000, v241
	v_lshlrev_b32_e32 v178, 16, v242
	v_and_b32_e32 v179, 0xffff0000, v242
	v_lshlrev_b32_e32 v180, 16, v243
	v_and_b32_e32 v181, 0xffff0000, v243
	v_pk_add_f32 v[62:63], v[62:63], v[166:167]
	v_pk_add_f32 v[64:65], v[64:65], v[168:169]
	v_pk_add_f32 v[58:59], v[58:59], v[170:171]
	v_pk_add_f32 v[60:61], v[60:61], v[172:173]
	v_pk_add_f32 v[54:55], v[54:55], v[174:175]
	v_pk_add_f32 v[56:57], v[56:57], v[176:177]
	v_pk_add_f32 v[50:51], v[50:51], v[178:179]
	v_pk_add_f32 v[52:53], v[52:53], v[180:181]
	v_cvt_pk_bf16_f32 v166, v62, v63
	v_cvt_pk_bf16_f32 v167, v64, v65
	v_cvt_pk_bf16_f32 v168, v58, v59
	v_cvt_pk_bf16_f32 v169, v60, v61
	v_cvt_pk_bf16_f32 v170, v54, v55
	v_cvt_pk_bf16_f32 v171, v56, v57
	v_cvt_pk_bf16_f32 v172, v50, v51
	v_cvt_pk_bf16_f32 v173, v52, v53
	v_mul_f32_e32 v174, v62, v62
	v_mul_f32_e32 v175, v58, v58
	v_mul_f32_e32 v176, v54, v54
	v_mul_f32_e32 v177, v50, v50
	v_fmac_f32_e32 v174, v63, v63
	v_fmac_f32_e32 v175, v59, v59
	v_fmac_f32_e32 v176, v55, v55
	v_fmac_f32_e32 v177, v51, v51
	v_fmac_f32_e32 v174, v64, v64
	v_fmac_f32_e32 v175, v60, v60
	v_fmac_f32_e32 v176, v56, v56
	v_fmac_f32_e32 v177, v52, v52
	v_fmac_f32_e32 v174, v65, v65
	v_fmac_f32_e32 v175, v61, v61
	v_fmac_f32_e32 v176, v57, v57
	v_fmac_f32_e32 v177, v53, v53
	v_add_f32_e32 v174, v174, v175
	v_add_f32_e32 v176, v176, v177
	v_add_f32_e32 v178, v174, v176
	v_mov_b32_e32 v179, v178
	v_permlane16_swap_b32_e32 v166, v168
	v_permlane16_swap_b32_e32 v167, v169
	v_permlane32_swap_b32_e32 v179, v178
	v_permlane16_swap_b32_e32 v170, v172
	v_permlane16_swap_b32_e32 v171, v173
	v_add_u32_e32 v253, 0x40000, v252
	global_store_dwordx4 v253, v[166:169], s[14:15]
	global_store_dwordx4 v253, v[170:173], s[14:15] offset:256
	v_add_f32_e32 v178, v178, v179
	v_mov_b32_e32 v179, v178
	v_add_u32_e32 v189, 0x2000, v189
	s_nop 0
	v_permlane16_swap_b32_e32 v179, v178
	v_add_f32_e32 v178, v178, v179
	s_and_saveexec_b64 s[30:31], s[8:9]
	global_store_dword v189, v178, s[16:17]
	s_or_b64 exec, exec, s[30:31]
	s_waitcnt vmcnt(14)
; __device__ __forceinline__ float bf_lo(unsigned u) { return __uint_as_float(u << 16); }
; __device__ __forceinline__ float bf_hi(unsigned u) { return __uint_as_float(u & 0xffff0000u); }
; __device__ __forceinline__ unsigned pk_bf16(float lo, float hi) { const f32x2 v = {lo, hi}; const bf16x2_t b = __builtin_convertvector(v, bf16x2_t); return __builtin_bit_cast(unsigned, b); }
;     __device__ __forceinline__ void operator()(const f32x4 (&acc)[2][2][4][2], const pg8::Unit& u, int wr, int wc, int fr, int fq) const {
;     ...
;                     for (int bj = 0; bj < 2; ++bj)
; #pragma unroll
;                         for (int n = 0; n < 2; ++n) { const u32x2 w = *(const u32x2*)(XB + off + bj * 128 + n * 16); r4[bj][n] = (f32x4){bf_lo(w.x), bf_hi(w.x), bf_lo(w.y), bf_hi(w.y)}; }
;                 }
; #pragma unroll
;                 for (int bj = 0; bj < 2; ++bj)
; #pragma unroll
;                     for (int n = 0; n < 2; ++n) { const f32x4 x4 = r4[bj][n] + acc[ai][bj][m][n];
;                         q += (x4[0] * x4[0] + x4[1] * x4[1]) + (x4[2] * x4[2] + x4[3] * x4[3]);
;                         u32x2 w; w.x = pk_bf16(x4[0], x4[1]); w.y = pk_bf16(x4[2], x4[3]); *(u32x2*)(XB + off + bj * 128 + n * 16) = w; }
;                 q += __shfl_xor(q, 16); q += __shfl_xor(q, 32);
;                 if (fq == 0) ssq[(size_t)row * 16 + u.pn * 4 + wc] = q;
	v_permlane16_swap_b32_e32 v244, v246
	v_permlane16_swap_b32_e32 v245, v247
	v_permlane16_swap_b32_e32 v248, v250
	v_permlane16_swap_b32_e32 v249, v251
	v_lshlrev_b32_e32 v166, 16, v244
	v_and_b32_e32 v167, 0xffff0000, v244
	v_lshlrev_b32_e32 v168, 16, v245
	v_and_b32_e32 v169, 0xffff0000, v245
	v_lshlrev_b32_e32 v170, 16, v246
	v_and_b32_e32 v171, 0xffff0000, v246
	v_lshlrev_b32_e32 v172, 16, v247
	v_and_b32_e32 v173, 0xffff0000, v247
	v_lshlrev_b32_e32 v174, 16, v248
	v_and_b32_e32 v175, 0xffff0000, v248
	v_lshlrev_b32_e32 v176, 16, v249
	v_and_b32_e32 v177, 0xffff0000, v249
	v_lshlrev_b32_e32 v178, 16, v250
	v_and_b32_e32 v179, 0xffff0000, v250
	v_lshlrev_b32_e32 v180, 16, v251
	v_and_b32_e32 v181, 0xffff0000, v251
	v_pk_add_f32 v[46:47], v[46:47], v[166:167]
	v_pk_add_f32 v[48:49], v[48:49], v[168:169]
	v_pk_add_f32 v[42:43], v[42:43], v[170:171]
	v_pk_add_f32 v[44:45], v[44:45], v[172:173]
	v_pk_add_f32 v[38:39], v[38:39], v[174:175]
	v_pk_add_f32 v[40:41], v[40:41], v[176:177]
	v_pk_add_f32 v[34:35], v[34:35], v[178:179]
	v_pk_add_f32 v[36:37], v[36:37], v[180:181]
	v_cvt_pk_bf16_f32 v166, v46, v47
	v_cvt_pk_bf16_f32 v167, v48, v49
	v_cvt_pk_bf16_f32 v168, v42, v43
	v_cvt_pk_bf16_f32 v169, v44, v45
	v_cvt_pk_bf16_f32 v170, v38, v39
	v_cvt_pk_bf16_f32 v171, v40, v41
	v_cvt_pk_bf16_f32 v172, v34, v35
	v_cvt_pk_bf16_f32 v173, v36, v37
	v_mul_f32_e32 v174, v46, v46
	v_mul_f32_e32 v175, v42, v42
	v_mul_f32_e32 v176, v38, v38
	v_mul_f32_e32 v177, v34, v34
	v_fmac_f32_e32 v174, v47, v47
	v_fmac_f32_e32 v175, v43, v43
	v_fmac_f32_e32 v176, v39, v39
	v_fmac_f32_e32 v177, v35, v35
	v_fmac_f32_e32 v174, v48, v48
	v_fmac_f32_e32 v175, v44, v44
	v_fmac_f32_e32 v176, v40, v40
	v_fmac_f32_e32 v177, v36, v36
	v_fmac_f32_e32 v174, v49, v49
	v_fmac_f32_e32 v175, v45, v45
	v_fmac_f32_e32 v176, v41, v41
	v_fmac_f32_e32 v177, v37, v37
	v_add_f32_e32 v174, v174, v175
	v_add_f32_e32 v176, v176, v177
	v_add_f32_e32 v178, v174, v176
	v_mov_b32_e32 v179, v178
	v_permlane16_swap_b32_e32 v166, v168
	v_permlane16_swap_b32_e32 v167, v169
	v_permlane32_swap_b32_e32 v179, v178
	v_permlane16_swap_b32_e32 v170, v172
	v_permlane16_swap_b32_e32 v171, v173
	v_add_u32_e32 v253, 0x48000, v252
	global_store_dwordx4 v253, v[166:169], s[14:15]
	global_store_dwordx4 v253, v[170:173], s[14:15] offset:256
	v_add_f32_e32 v178, v178, v179
	v_mov_b32_e32 v179, v178
	s_nop 0
	s_nop 0
	v_permlane16_swap_b32_e32 v179, v178
	v_add_f32_e32 v178, v178, v179
	s_and_saveexec_b64 s[30:31], s[8:9]
	global_store_dword v189, v178, s[16:17] offset:1024
	s_or_b64 exec, exec, s[30:31]
	s_waitcnt vmcnt(14)
; __device__ __forceinline__ float bf_lo(unsigned u) { return __uint_as_float(u << 16); }
; __device__ __forceinline__ float bf_hi(unsigned u) { return __uint_as_float(u & 0xffff0000u); }
; __device__ __forceinline__ unsigned pk_bf16(float lo, float hi) { const f32x2 v = {lo, hi}; const bf16x2_t b = __builtin_convertvector(v, bf16x2_t); return __builtin_bit_cast(unsigned, b); }
;     __device__ __forceinline__ void operator()(const f32x4 (&acc)[2][2][4][2], const pg8::Unit& u, int wr, int wc, int fr, int fq) const {
;     ...
;                     for (int bj = 0; bj < 2; ++bj)
; #pragma unroll
;                         for (int n = 0; n < 2; ++n) { const u32x2 w = *(const u32x2*)(XB + off + bj * 128 + n * 16); r4[bj][n] = (f32x4){bf_lo(w.x), bf_hi(w.x), bf_lo(w.y), bf_hi(w.y)}; }
;                 }
; #pragma unroll
;                 for (int bj = 0; bj < 2; ++bj)
; #pragma unroll
;                     for (int n = 0; n < 2; ++n) { const f32x4 x4 = r4[bj][n] + acc[ai][bj][m][n];
;                         q += (x4[0] * x4[0] + x4[1] * x4[1]) + (x4[2] * x4[2] + x4[3] * x4[3]);
;                         u32x2 w; w.x = pk_bf16(x4[0], x4[1]); w.y = pk_bf16(x4[2], x4[3]); *(u32x2*)(XB + off + bj * 128 + n * 16) = w; }
;                 q += __shfl_xor(q, 16); q += __shfl_xor(q, 32);
;                 if (fq == 0) ssq[(size_t)row * 16 + u.pn * 4 + wc] = q;
	v_permlane16_swap_b32_e32 v204, v206
	v_permlane16_swap_b32_e32 v205, v207
	v_permlane16_swap_b32_e32 v208, v210
	v_permlane16_swap_b32_e32 v209, v211
	v_lshlrev_b32_e32 v166, 16, v204
	v_and_b32_e32 v167, 0xffff0000, v204
	v_lshlrev_b32_e32 v168, 16, v205
	v_and_b32_e32 v169, 0xffff0000, v205
	v_lshlrev_b32_e32 v170, 16, v206
	v_and_b32_e32 v171, 0xffff0000, v206
	v_lshlrev_b32_e32 v172, 16, v207
	v_and_b32_e32 v173, 0xffff0000, v207
	v_lshlrev_b32_e32 v174, 16, v208
	v_and_b32_e32 v175, 0xffff0000, v208
	v_lshlrev_b32_e32 v176, 16, v209
	v_and_b32_e32 v177, 0xffff0000, v209
	v_lshlrev_b32_e32 v178, 16, v210
	v_and_b32_e32 v179, 0xffff0000, v210
	v_lshlrev_b32_e32 v180, 16, v211
	v_and_b32_e32 v181, 0xffff0000, v211
	v_pk_add_f32 v[30:31], v[30:31], v[166:167]
	v_pk_add_f32 v[32:33], v[32:33], v[168:169]
	v_pk_add_f32 v[26:27], v[26:27], v[170:171]
	v_pk_add_f32 v[28:29], v[28:29], v[172:173]
	v_pk_add_f32 v[22:23], v[22:23], v[174:175]
	v_pk_add_f32 v[24:25], v[24:25], v[176:177]
	v_pk_add_f32 v[18:19], v[18:19], v[178:179]
	v_pk_add_f32 v[20:21], v[20:21], v[180:181]
	v_cvt_pk_bf16_f32 v166, v30, v31
	v_cvt_pk_bf16_f32 v167, v32, v33
	v_cvt_pk_bf16_f32 v168, v26, v27
	v_cvt_pk_bf16_f32 v169, v28, v29
	v_cvt_pk_bf16_f32 v170, v22, v23
	v_cvt_pk_bf16_f32 v171, v24, v25
	v_cvt_pk_bf16_f32 v172, v18, v19
	v_cvt_pk_bf16_f32 v173, v20, v21
	v_mul_f32_e32 v174, v30, v30
	v_mul_f32_e32 v175, v26, v26
	v_mul_f32_e32 v176, v22, v22
	v_mul_f32_e32 v177, v18, v18
	v_fmac_f32_e32 v174, v31, v31
	v_fmac_f32_e32 v175, v27, v27
	v_fmac_f32_e32 v176, v23, v23
	v_fmac_f32_e32 v177, v19, v19
	v_fmac_f32_e32 v174, v32, v32
	v_fmac_f32_e32 v175, v28, v28
	v_fmac_f32_e32 v176, v24, v24
	v_fmac_f32_e32 v177, v20, v20
	v_fmac_f32_e32 v174, v33, v33
	v_fmac_f32_e32 v175, v29, v29
	v_fmac_f32_e32 v176, v25, v25
	v_fmac_f32_e32 v177, v21, v21
	v_add_f32_e32 v174, v174, v175
	v_add_f32_e32 v176, v176, v177
	v_add_f32_e32 v178, v174, v176
	v_mov_b32_e32 v179, v178
	v_permlane16_swap_b32_e32 v166, v168
	v_permlane16_swap_b32_e32 v167, v169
	v_permlane32_swap_b32_e32 v179, v178
	v_permlane16_swap_b32_e32 v170, v172
	v_permlane16_swap_b32_e32 v171, v173
	v_add_u32_e32 v253, 0x50000, v252
	global_store_dwordx4 v253, v[166:169], s[14:15]
	global_store_dwordx4 v253, v[170:173], s[14:15] offset:256
	v_add_f32_e32 v178, v178, v179
	v_mov_b32_e32 v179, v178
	s_nop 0
	s_nop 0
	v_permlane16_swap_b32_e32 v179, v178
	v_add_f32_e32 v178, v178, v179
	s_and_saveexec_b64 s[30:31], s[8:9]
	global_store_dword v189, v178, s[16:17] offset:2048
	s_or_b64 exec, exec, s[30:31]
	s_waitcnt vmcnt(12)
	v_permlane16_swap_b32_e32 v212, v214
	v_permlane16_swap_b32_e32 v213, v215
	v_permlane16_swap_b32_e32 v216, v218
	v_permlane16_swap_b32_e32 v217, v219
	v_lshlrev_b32_e32 v166, 16, v212
	v_and_b32_e32 v167, 0xffff0000, v212
	v_lshlrev_b32_e32 v168, 16, v213
	v_and_b32_e32 v169, 0xffff0000, v213
	v_lshlrev_b32_e32 v170, 16, v214
	v_and_b32_e32 v171, 0xffff0000, v214
	v_lshlrev_b32_e32 v172, 16, v215
	v_and_b32_e32 v173, 0xffff0000, v215
	v_lshlrev_b32_e32 v174, 16, v216
	v_and_b32_e32 v175, 0xffff0000, v216
	v_lshlrev_b32_e32 v176, 16, v217
	v_and_b32_e32 v177, 0xffff0000, v217
	v_lshlrev_b32_e32 v178, 16, v218
	v_and_b32_e32 v179, 0xffff0000, v218
	v_lshlrev_b32_e32 v180, 16, v219
	v_and_b32_e32 v181, 0xffff0000, v219
	v_pk_add_f32 v[14:15], v[14:15], v[166:167]
	v_pk_add_f32 v[16:17], v[16:17], v[168:169]
	v_pk_add_f32 v[10:11], v[10:11], v[170:171]
	v_pk_add_f32 v[12:13], v[12:13], v[172:173]
	v_pk_add_f32 v[6:7], v[6:7], v[174:175]
	v_pk_add_f32 v[8:9], v[8:9], v[176:177]
	v_pk_add_f32 v[2:3], v[2:3], v[178:179]
	v_pk_add_f32 v[4:5], v[4:5], v[180:181]
	v_cvt_pk_bf16_f32 v166, v14, v15
	v_cvt_pk_bf16_f32 v167, v16, v17
	v_cvt_pk_bf16_f32 v168, v10, v11
	v_cvt_pk_bf16_f32 v169, v12, v13
	v_cvt_pk_bf16_f32 v170, v6, v7
	v_cvt_pk_bf16_f32 v171, v8, v9
	v_cvt_pk_bf16_f32 v172, v2, v3
	v_cvt_pk_bf16_f32 v173, v4, v5
	v_mul_f32_e32 v174, v14, v14
	v_mul_f32_e32 v175, v10, v10
	v_mul_f32_e32 v176, v6, v6
	v_mul_f32_e32 v177, v2, v2
	v_fmac_f32_e32 v174, v15, v15
	v_fmac_f32_e32 v175, v11, v11
	v_fmac_f32_e32 v176, v7, v7
	v_fmac_f32_e32 v177, v3, v3
	v_fmac_f32_e32 v174, v16, v16
	v_fmac_f32_e32 v175, v12, v12
	v_fmac_f32_e32 v176, v8, v8
	v_fmac_f32_e32 v177, v4, v4
	v_fmac_f32_e32 v174, v17, v17
	v_fmac_f32_e32 v175, v13, v13
	v_fmac_f32_e32 v176, v9, v9
	v_fmac_f32_e32 v177, v5, v5
	v_add_f32_e32 v174, v174, v175
	v_add_f32_e32 v176, v176, v177
	v_add_f32_e32 v178, v174, v176
	v_mov_b32_e32 v179, v178
	v_permlane16_swap_b32_e32 v166, v168
	v_permlane16_swap_b32_e32 v167, v169
	v_permlane32_swap_b32_e32 v179, v178
	v_permlane16_swap_b32_e32 v170, v172
	v_permlane16_swap_b32_e32 v171, v173
	v_add_u32_e32 v253, 0x58000, v252
	global_store_dwordx4 v253, v[166:169], s[14:15]
	global_store_dwordx4 v253, v[170:173], s[14:15] offset:256
	v_add_f32_e32 v178, v178, v179
	v_mov_b32_e32 v179, v178
	s_nop 0
	s_nop 0
	v_permlane16_swap_b32_e32 v179, v178
	v_add_f32_e32 v178, v178, v179
	s_and_saveexec_b64 s[30:31], s[8:9]
	global_store_dword v189, v178, s[16:17] offset:3072
	s_or_b64 exec, exec, s[30:31]

; __device__ __forceinline__ float bf_lo(unsigned u) { return __uint_as_float(u << 16); }
; __device__ __forceinline__ float bf_hi(unsigned u) { return __uint_as_float(u & 0xffff0000u); }
; __device__ __forceinline__ unsigned pk_bf16(float lo, float hi) { const f32x2 v = {lo, hi}; const bf16x2_t b = __builtin_convertvector(v, bf16x2_t); return __builtin_bit_cast(unsigned, b); }
;     __device__ __forceinline__ void operator()(const f32x4 (&acc)[2][2][4][2], const pg8::Unit& u, int wr, int wc, int fr, int fq) const {
;     ...
;         const int row0 = u.pm * 256 + wr * 64 + fr, col0 = u.pn * 256 + wc * 32 + 4 * fq;
;         const bool rf32 = (rp != nullptr) && (u.pm < MP / 256);
; #pragma unroll
;         for (int ai = 0; ai < 2; ++ai)
; #pragma unroll
;             for (int m = 0; m < 4; ++m) {
;                 const int row = row0 + ai * 128 + m * 16; const size_t off = (size_t)row * DM + col0; float q = 0.f;
;                 f32x4 r4[2][2];
;                 if (rf32) {
; #pragma unroll
;                     for (int bj = 0; bj < 2; ++bj)
; #pragma unroll
;                         for (int n = 0; n < 2; ++n) r4[bj][n] = *(const f32x4*)(rp + off + bj * 128 + n * 16);
;                 } else {
; #pragma unroll
;                     for (int bj = 0; bj < 2; ++bj)
; #pragma unroll
;                         for (int n = 0; n < 2; ++n) { const u32x2 w = *(const u32x2*)(XB + off + bj * 128 + n * 16); r4[bj][n] = (f32x4){bf_lo(w.x), bf_hi(w.x), bf_lo(w.y), bf_hi(w.y)}; }
;                 }
; #pragma unroll
;                 for (int bj = 0; bj < 2; ++bj)
; #pragma unroll
;                     for (int n = 0; n < 2; ++n) { const f32x4 x4 = r4[bj][n] + acc[ai][bj][m][n];
;                         q += (x4[0] * x4[0] + x4[1] * x4[1]) + (x4[2] * x4[2] + x4[3] * x4[3]);
;                         u32x2 w; w.x = pk_bf16(x4[0], x4[1]); w.y = pk_bf16(x4[2], x4[3]); *(u32x2*)(XB + off + bj * 128 + n * 16) = w; }
;                 q += __shfl_xor(q, 16); q += __shfl_xor(q, 32);
;                 if (fq == 0) ssq[(size_t)row * 16 + u.pn * 4 + wc] = q;
.LBB0_1893:
	s_lshl_b32 s4, s47, 8
	v_mov_b32_e32 v158, v1
	s_add_i32 s4, s4, s40
	s_lshl_b32 s22, s46, 2
	v_add_u32_e32 v160, s4, v158
	v_ashrrev_i32_e32 v161, 31, v160
	v_lshl_or_b32 v158, s46, 8, v163
	v_lshlrev_b64 v[166:167], 11, v[160:161]
	v_ashrrev_i32_e32 v159, 31, v158
	v_lshl_add_u64 v[166:167], s[14:15], 0, v[166:167]
	v_lshl_add_u64 v[166:167], v[158:159], 1, v[166:167]
	s_ashr_i32 s23, s22, 31
	v_lshlrev_b32_e32 v252, 11, v160
	v_lshl_add_u32 v252, v158, 1, v252
	v_bfe_u32 v253, v190, 4, 1
	v_mul_u32_u24_e32 v253, 24, v253
	v_add_u32_e32 v252, v252, v253
	s_lshl_b32 s88, s39, 2
	v_lshl_add_u32 v189, v160, 6, s88
	v_lshl_add_u32 v189, s22, 2, v189
	global_load_dwordx4 v[204:207], v252, s[14:15]
	global_load_dwordx4 v[208:211], v252, s[14:15] offset:256
	v_add_u32_e32 v253, 0x8000, v252
	global_load_dwordx4 v[212:215], v253, s[14:15]
	global_load_dwordx4 v[216:219], v253, s[14:15] offset:256
	v_add_u32_e32 v253, 0x10000, v252
	global_load_dwordx4 v[220:223], v253, s[14:15]
	global_load_dwordx4 v[224:227], v253, s[14:15] offset:256
	v_add_u32_e32 v253, 0x18000, v252
	global_load_dwordx4 v[228:231], v253, s[14:15]
	global_load_dwordx4 v[232:235], v253, s[14:15] offset:256
	v_add_u32_e32 v253, 0x40000, v252
	global_load_dwordx4 v[236:239], v253, s[14:15]
	global_load_dwordx4 v[240:243], v253, s[14:15] offset:256
	v_add_u32_e32 v253, 0x48000, v252
	global_load_dwordx4 v[244:247], v253, s[14:15]
	global_load_dwordx4 v[248:251], v253, s[14:15] offset:256
	s_waitcnt vmcnt(10)
	v_permlane16_swap_b32_e32 v204, v206
	v_permlane16_swap_b32_e32 v205, v207
	v_permlane16_swap_b32_e32 v208, v210
	v_permlane16_swap_b32_e32 v209, v211
	v_lshlrev_b32_e32 v166, 16, v204
	v_and_b32_e32 v167, 0xffff0000, v204
	v_lshlrev_b32_e32 v168, 16, v205
	v_and_b32_e32 v169, 0xffff0000, v205
	v_lshlrev_b32_e32 v170, 16, v206
	v_and_b32_e32 v171, 0xffff0000, v206
	v_lshlrev_b32_e32 v172, 16, v207
	v_and_b32_e32 v173, 0xffff0000, v207
	v_lshlrev_b32_e32 v174, 16, v208
	v_and_b32_e32 v175, 0xffff0000, v208
	v_lshlrev_b32_e32 v176, 16, v209
	v_and_b32_e32 v177, 0xffff0000, v209
	v_lshlrev_b32_e32 v178, 16, v210
	v_and_b32_e32 v179, 0xffff0000, v210
	v_lshlrev_b32_e32 v180, 16, v211
	v_and_b32_e32 v181, 0xffff0000, v211
	v_pk_add_f32 v[126:127], v[126:127], v[166:167]
	v_pk_add_f32 v[128:129], v[128:129], v[168:169]
	v_pk_add_f32 v[122:123], v[122:123], v[170:171]
	v_pk_add_f32 v[124:125], v[124:125], v[172:173]
	v_pk_add_f32 v[118:119], v[118:119], v[174:175]
	v_pk_add_f32 v[120:121], v[120:121], v[176:177]
	v_pk_add_f32 v[114:115], v[114:115], v[178:179]
	v_pk_add_f32 v[116:117], v[116:117], v[180:181]
	v_add_u32_e32 v253, 0x50000, v252
	global_load_dwordx4 v[204:207], v253, s[14:15]
	global_load_dwordx4 v[208:211], v253, s[14:15] offset:256
	v_cvt_pk_bf16_f32 v166, v126, v127
	v_cvt_pk_bf16_f32 v167, v128, v129
	v_cvt_pk_bf16_f32 v168, v122, v123
	v_cvt_pk_bf16_f32 v169, v124, v125
	v_cvt_pk_bf16_f32 v170, v118, v119
	v_cvt_pk_bf16_f32 v171, v120, v121
	v_cvt_pk_bf16_f32 v172, v114, v115
	v_cvt_pk_bf16_f32 v173, v116, v117
	v_mul_f32_e32 v174, v126, v126
	v_mul_f32_e32 v175, v122, v122
	v_mul_f32_e32 v176, v118, v118
	v_mul_f32_e32 v177, v114, v114
	v_fmac_f32_e32 v174, v127, v127
	v_fmac_f32_e32 v175, v123, v123
	v_fmac_f32_e32 v176, v119, v119
	v_fmac_f32_e32 v177, v115, v115
	v_fmac_f32_e32 v174, v128, v128
	v_fmac_f32_e32 v175, v124, v124
	v_fmac_f32_e32 v176, v120, v120
	v_fmac_f32_e32 v177, v116, v116
	v_fmac_f32_e32 v174, v129, v129
	v_fmac_f32_e32 v175, v125, v125
	v_fmac_f32_e32 v176, v121, v121
	v_fmac_f32_e32 v177, v117, v117
	v_add_f32_e32 v174, v174, v175
	v_add_f32_e32 v176, v176, v177
	v_add_f32_e32 v178, v174, v176
	v_mov_b32_e32 v179, v178
	v_permlane16_swap_b32_e32 v166, v168
	v_permlane16_swap_b32_e32 v167, v169
	v_permlane32_swap_b32_e32 v179, v178
	v_permlane16_swap_b32_e32 v170, v172
	v_permlane16_swap_b32_e32 v171, v173
	global_store_dwordx4 v252, v[166:169], s[14:15]
	global_store_dwordx4 v252, v[170:173], s[14:15] offset:256
	v_add_f32_e32 v178, v178, v179
	v_mov_b32_e32 v179, v178
	s_nop 0
	s_nop 0
	v_permlane16_swap_b32_e32 v179, v178
	v_add_f32_e32 v178, v178, v179
	s_and_saveexec_b64 s[24:25], s[6:7]
	global_store_dword v189, v178, s[16:17]
	s_or_b64 exec, exec, s[24:25]
	s_waitcnt vmcnt(12)
; __device__ __forceinline__ float bf_lo(unsigned u) { return __uint_as_float(u << 16); }
; __device__ __forceinline__ float bf_hi(unsigned u) { return __uint_as_float(u & 0xffff0000u); }
; __device__ __forceinline__ unsigned pk_bf16(float lo, float hi) { const f32x2 v = {lo, hi}; const bf16x2_t b = __builtin_convertvector(v, bf16x2_t); return __builtin_bit_cast(unsigned, b); }
;     __device__ __forceinline__ void operator()(const f32x4 (&acc)[2][2][4][2], const pg8::Unit& u, int wr, int wc, int fr, int fq) const {
;     ...
;                     for (int bj = 0; bj < 2; ++bj)
; #pragma unroll
;                         for (int n = 0; n < 2; ++n) { const u32x2 w = *(const u32x2*)(XB + off + bj * 128 + n * 16); r4[bj][n] = (f32x4){bf_lo(w.x), bf_hi(w.x), bf_lo(w.y), bf_hi(w.y)}; }
;                 }
; #pragma unroll
;                 for (int bj = 0; bj < 2; ++bj)
; #pragma unroll
;                     for (int n = 0; n < 2; ++n) { const f32x4 x4 = r4[bj][n] + acc[ai][bj][m][n];
;                         q += (x4[0] * x4[0] + x4[1] * x4[1]) + (x4[2] * x4[2] + x4[3] * x4[3]);
;                         u32x2 w; w.x = pk_bf16(x4[0], x4[1]); w.y = pk_bf16(x4[2], x4[3]); *(u32x2*)(XB + off + bj * 128 + n * 16) = w; }
;                 q += __shfl_xor(q, 16); q += __shfl_xor(q, 32);
;                 if (fq == 0) ssq[(size_t)row * 16 + u.pn * 4 + wc] = q;
	v_permlane16_swap_b32_e32 v212, v214
	v_permlane16_swap_b32_e32 v213, v215
	v_permlane16_swap_b32_e32 v216, v218
	v_permlane16_swap_b32_e32 v217, v219
	v_lshlrev_b32_e32 v166, 16, v212
	v_and_b32_e32 v167, 0xffff0000, v212
	v_lshlrev_b32_e32 v168, 16, v213
	v_and_b32_e32 v169, 0xffff0000, v213
	v_lshlrev_b32_e32 v170, 16, v214
	v_and_b32_e32 v171, 0xffff0000, v214
	v_lshlrev_b32_e32 v172, 16, v215
	v_and_b32_e32 v173, 0xffff0000, v215
	v_lshlrev_b32_e32 v174, 16, v216
	v_and_b32_e32 v175, 0xffff0000, v216
	v_lshlrev_b32_e32 v176, 16, v217
	v_and_b32_e32 v177, 0xffff0000, v217
	v_lshlrev_b32_e32 v178, 16, v218
	v_and_b32_e32 v179, 0xffff0000, v218
	v_lshlrev_b32_e32 v180, 16, v219
	v_and_b32_e32 v181, 0xffff0000, v219
	v_pk_add_f32 v[110:111], v[110:111], v[166:167]
	v_pk_add_f32 v[112:113], v[112:113], v[168:169]
	v_pk_add_f32 v[106:107], v[106:107], v[170:171]
	v_pk_add_f32 v[108:109], v[108:109], v[172:173]
	v_pk_add_f32 v[102:103], v[102:103], v[174:175]
	v_pk_add_f32 v[104:105], v[104:105], v[176:177]
	v_pk_add_f32 v[98:99], v[98:99], v[178:179]
	v_pk_add_f32 v[100:101], v[100:101], v[180:181]
	v_add_u32_e32 v253, 0x58000, v252
	global_load_dwordx4 v[212:215], v253, s[14:15]
	global_load_dwordx4 v[216:219], v253, s[14:15] offset:256
	v_cvt_pk_bf16_f32 v166, v110, v111
	v_cvt_pk_bf16_f32 v167, v112, v113
	v_cvt_pk_bf16_f32 v168, v106, v107
	v_cvt_pk_bf16_f32 v169, v108, v109
	v_cvt_pk_bf16_f32 v170, v102, v103
	v_cvt_pk_bf16_f32 v171, v104, v105
	v_cvt_pk_bf16_f32 v172, v98, v99
	v_cvt_pk_bf16_f32 v173, v100, v101
	v_mul_f32_e32 v174, v110, v110
	v_mul_f32_e32 v175, v106, v106
	v_mul_f32_e32 v176, v102, v102
	v_mul_f32_e32 v177, v98, v98
	v_fmac_f32_e32 v174, v111, v111
	v_fmac_f32_e32 v175, v107, v107
	v_fmac_f32_e32 v176, v103, v103
	v_fmac_f32_e32 v177, v99, v99
	v_fmac_f32_e32 v174, v112, v112
	v_fmac_f32_e32 v175, v108, v108
	v_fmac_f32_e32 v176, v104, v104
	v_fmac_f32_e32 v177, v100, v100
	v_fmac_f32_e32 v174, v113, v113
	v_fmac_f32_e32 v175, v109, v109
	v_fmac_f32_e32 v176, v105, v105
	v_fmac_f32_e32 v177, v101, v101
	v_add_f32_e32 v174, v174, v175
	v_add_f32_e32 v176, v176, v177
	v_add_f32_e32 v178, v174, v176
	v_mov_b32_e32 v179, v178
	v_permlane16_swap_b32_e32 v166, v168
	v_permlane16_swap_b32_e32 v167, v169
	v_permlane32_swap_b32_e32 v179, v178
	v_permlane16_swap_b32_e32 v170, v172
	v_permlane16_swap_b32_e32 v171, v173
	v_add_u32_e32 v253, 0x8000, v252
	global_store_dwordx4 v253, v[166:169], s[14:15]
	global_store_dwordx4 v253, v[170:173], s[14:15] offset:256
	v_add_f32_e32 v178, v178, v179
	v_mov_b32_e32 v179, v178
	s_nop 0
	s_nop 0
	v_permlane16_swap_b32_e32 v179, v178
	v_add_f32_e32 v178, v178, v179
	s_and_saveexec_b64 s[24:25], s[6:7]
	global_store_dword v189, v178, s[16:17] offset:1024
	s_or_b64 exec, exec, s[24:25]
	s_waitcnt vmcnt(14)
	v_permlane16_swap_b32_e32 v220, v222
	v_permlane16_swap_b32_e32 v221, v223
	v_permlane16_swap_b32_e32 v224, v226
	v_permlane16_swap_b32_e32 v225, v227
	v_lshlrev_b32_e32 v166, 16, v220
	v_and_b32_e32 v167, 0xffff0000, v220
	v_lshlrev_b32_e32 v168, 16, v221
	v_and_b32_e32 v169, 0xffff0000, v221
	v_lshlrev_b32_e32 v170, 16, v222
	v_and_b32_e32 v171, 0xffff0000, v222
	v_lshlrev_b32_e32 v172, 16, v223
	v_and_b32_e32 v173, 0xffff0000, v223
	v_lshlrev_b32_e32 v174, 16, v224
	v_and_b32_e32 v175, 0xffff0000, v224
	v_lshlrev_b32_e32 v176, 16, v225
	v_and_b32_e32 v177, 0xffff0000, v225
	v_lshlrev_b32_e32 v178, 16, v226
	v_and_b32_e32 v179, 0xffff0000, v226
	v_lshlrev_b32_e32 v180, 16, v227
	v_and_b32_e32 v181, 0xffff0000, v227
	v_pk_add_f32 v[94:95], v[94:95], v[166:167]
	v_pk_add_f32 v[96:97], v[96:97], v[168:169]
	v_pk_add_f32 v[90:91], v[90:91], v[170:171]
	v_pk_add_f32 v[92:93], v[92:93], v[172:173]
	v_pk_add_f32 v[86:87], v[86:87], v[174:175]
	v_pk_add_f32 v[88:89], v[88:89], v[176:177]
	v_pk_add_f32 v[82:83], v[82:83], v[178:179]
	v_pk_add_f32 v[84:85], v[84:85], v[180:181]
	v_cvt_pk_bf16_f32 v166, v94, v95
	v_cvt_pk_bf16_f32 v167, v96, v97
	v_cvt_pk_bf16_f32 v168, v90, v91
	v_cvt_pk_bf16_f32 v169, v92, v93
	v_cvt_pk_bf16_f32 v170, v86, v87
	v_cvt_pk_bf16_f32 v171, v88, v89
	v_cvt_pk_bf16_f32 v172, v82, v83
	v_cvt_pk_bf16_f32 v173, v84, v85
	v_mul_f32_e32 v174, v94, v94
	v_mul_f32_e32 v175, v90, v90
	v_mul_f32_e32 v176, v86, v86
	v_mul_f32_e32 v177, v82, v82
	v_fmac_f32_e32 v174, v95, v95
	v_fmac_f32_e32 v175, v91, v91
	v_fmac_f32_e32 v176, v87, v87
	v_fmac_f32_e32 v177, v83, v83
	v_fmac_f32_e32 v174, v96, v96
	v_fmac_f32_e32 v175, v92, v92
	v_fmac_f32_e32 v176, v88, v88
	v_fmac_f32_e32 v177, v84, v84
	v_fmac_f32_e32 v174, v97, v97
	v_fmac_f32_e32 v175, v93, v93
	v_fmac_f32_e32 v176, v89, v89
	v_fmac_f32_e32 v177, v85, v85
	v_add_f32_e32 v174, v174, v175
	v_add_f32_e32 v176, v176, v177
	v_add_f32_e32 v178, v174, v176
	v_mov_b32_e32 v179, v178
	v_permlane16_swap_b32_e32 v166, v168
	v_permlane16_swap_b32_e32 v167, v169
	v_permlane32_swap_b32_e32 v179, v178
	v_permlane16_swap_b32_e32 v170, v172
	v_permlane16_swap_b32_e32 v171, v173
	v_add_u32_e32 v253, 0x10000, v252
	global_store_dwordx4 v253, v[166:169], s[14:15]
	global_store_dwordx4 v253, v[170:173], s[14:15] offset:256
	v_add_f32_e32 v178, v178, v179
	v_mov_b32_e32 v179, v178
	s_nop 0
	s_nop 0
	v_permlane16_swap_b32_e32 v179, v178
	v_add_f32_e32 v178, v178, v179
	s_and_saveexec_b64 s[24:25], s[6:7]
	global_store_dword v189, v178, s[16:17] offset:2048
	s_or_b64 exec, exec, s[24:25]
	s_waitcnt vmcnt(14)
; __device__ __forceinline__ float bf_lo(unsigned u) { return __uint_as_float(u << 16); }
; __device__ __forceinline__ float bf_hi(unsigned u) { return __uint_as_float(u & 0xffff0000u); }
; __device__ __forceinline__ unsigned pk_bf16(float lo, float hi) { const f32x2 v = {lo, hi}; const bf16x2_t b = __builtin_convertvector(v, bf16x2_t); return __builtin_bit_cast(unsigned, b); }
;     __device__ __forceinline__ void operator()(const f32x4 (&acc)[2][2][4][2], const pg8::Unit& u, int wr, int wc, int fr, int fq) const {
;     ...
;                     for (int bj = 0; bj < 2; ++bj)
; #pragma unroll
;                         for (int n = 0; n < 2; ++n) { const u32x2 w = *(const u32x2*)(XB + off + bj * 128 + n * 16); r4[bj][n] = (f32x4){bf_lo(w.x), bf_hi(w.x), bf_lo(w.y), bf_hi(w.y)}; }
;                 }
; #pragma unroll
;                 for (int bj = 0; bj < 2; ++bj)
; #pragma unroll
;                     for (int n = 0; n < 2; ++n) { const f32x4 x4 = r4[bj][n] + acc[ai][bj][m][n];
;                         q += (x4[0] * x4[0] + x4[1] * x4[1]) + (x4[2] * x4[2] + x4[3] * x4[3]);
;                         u32x2 w; w.x = pk_bf16(x4[0], x4[1]); w.y = pk_bf16(x4[2], x4[3]); *(u32x2*)(XB + off + bj * 128 + n * 16) = w; }
;                 q += __shfl_xor(q, 16); q += __shfl_xor(q, 32);
;                 if (fq == 0) ssq[(size_t)row * 16 + u.pn * 4 + wc] = q;
	v_permlane16_swap_b32_e32 v228, v230
	v_permlane16_swap_b32_e32 v229, v231
	v_permlane16_swap_b32_e32 v232, v234
	v_permlane16_swap_b32_e32 v233, v235
	v_lshlrev_b32_e32 v166, 16, v228
	v_and_b32_e32 v167, 0xffff0000, v228
	v_lshlrev_b32_e32 v168, 16, v229
	v_and_b32_e32 v169, 0xffff0000, v229
	v_lshlrev_b32_e32 v170, 16, v230
	v_and_b32_e32 v171, 0xffff0000, v230
	v_lshlrev_b32_e32 v172, 16, v231
	v_and_b32_e32 v173, 0xffff0000, v231
	v_lshlrev_b32_e32 v174, 16, v232
	v_and_b32_e32 v175, 0xffff0000, v232
	v_lshlrev_b32_e32 v176, 16, v233
	v_and_b32_e32 v177, 0xffff0000, v233
	v_lshlrev_b32_e32 v178, 16, v234
	v_and_b32_e32 v179, 0xffff0000, v234
	v_lshlrev_b32_e32 v180, 16, v235
	v_and_b32_e32 v181, 0xffff0000, v235
	v_pk_add_f32 v[78:79], v[78:79], v[166:167]
	v_pk_add_f32 v[80:81], v[80:81], v[168:169]
	v_pk_add_f32 v[74:75], v[74:75], v[170:171]
	v_pk_add_f32 v[76:77], v[76:77], v[172:173]
	v_pk_add_f32 v[70:71], v[70:71], v[174:175]
	v_pk_add_f32 v[72:73], v[72:73], v[176:177]
	v_pk_add_f32 v[66:67], v[66:67], v[178:179]
	v_pk_add_f32 v[68:69], v[68:69], v[180:181]
	v_cvt_pk_bf16_f32 v166, v78, v79
	v_cvt_pk_bf16_f32 v167, v80, v81
	v_cvt_pk_bf16_f32 v168, v74, v75
	v_cvt_pk_bf16_f32 v169, v76, v77
	v_cvt_pk_bf16_f32 v170, v70, v71
	v_cvt_pk_bf16_f32 v171, v72, v73
	v_cvt_pk_bf16_f32 v172, v66, v67
	v_cvt_pk_bf16_f32 v173, v68, v69
	v_mul_f32_e32 v174, v78, v78
	v_mul_f32_e32 v175, v74, v74
	v_mul_f32_e32 v176, v70, v70
	v_mul_f32_e32 v177, v66, v66
	v_fmac_f32_e32 v174, v79, v79
	v_fmac_f32_e32 v175, v75, v75
	v_fmac_f32_e32 v176, v71, v71
	v_fmac_f32_e32 v177, v67, v67
	v_fmac_f32_e32 v174, v80, v80
	v_fmac_f32_e32 v175, v76, v76
	v_fmac_f32_e32 v176, v72, v72
	v_fmac_f32_e32 v177, v68, v68
	v_fmac_f32_e32 v174, v81, v81
	v_fmac_f32_e32 v175, v77, v77
	v_fmac_f32_e32 v176, v73, v73
	v_fmac_f32_e32 v177, v69, v69
	v_add_f32_e32 v174, v174, v175
	v_add_f32_e32 v176, v176, v177
	v_add_f32_e32 v178, v174, v176
	v_mov_b32_e32 v179, v178
	v_permlane16_swap_b32_e32 v166, v168
	v_permlane16_swap_b32_e32 v167, v169
	v_permlane32_swap_b32_e32 v179, v178
	v_permlane16_swap_b32_e32 v170, v172
	v_permlane16_swap_b32_e32 v171, v173
	v_add_u32_e32 v253, 0x18000, v252
	global_store_dwordx4 v253, v[166:169], s[14:15]
	global_store_dwordx4 v253, v[170:173], s[14:15] offset:256
	v_add_f32_e32 v178, v178, v179
	v_mov_b32_e32 v179, v178
	s_nop 0
	s_nop 0
	v_permlane16_swap_b32_e32 v179, v178
	v_add_f32_e32 v178, v178, v179
	s_and_saveexec_b64 s[24:25], s[6:7]
	global_store_dword v189, v178, s[16:17] offset:3072
	s_or_b64 exec, exec, s[24:25]
	s_waitcnt vmcnt(14)
	v_permlane16_swap_b32_e32 v236, v238
	v_permlane16_swap_b32_e32 v237, v239
	v_permlane16_swap_b32_e32 v240, v242
	v_permlane16_swap_b32_e32 v241, v243
	v_lshlrev_b32_e32 v166, 16, v236
	v_and_b32_e32 v167, 0xffff0000, v236
	v_lshlrev_b32_e32 v168, 16, v237
	v_and_b32_e32 v169, 0xffff0000, v237
	v_lshlrev_b32_e32 v170, 16, v238
	v_and_b32_e32 v171, 0xffff0000, v238
	v_lshlrev_b32_e32 v172, 16, v239
	v_and_b32_e32 v173, 0xffff0000, v239
	v_lshlrev_b32_e32 v174, 16, v240
	v_and_b32_e32 v175, 0xffff0000, v240
	v_lshlrev_b32_e32 v176, 16, v241
	v_and_b32_e32 v177, 0xffff0000, v241
	v_lshlrev_b32_e32 v178, 16, v242
	v_and_b32_e32 v179, 0xffff0000, v242
	v_lshlrev_b32_e32 v180, 16, v243
	v_and_b32_e32 v181, 0xffff0000, v243
	v_pk_add_f32 v[62:63], v[62:63], v[166:167]
	v_pk_add_f32 v[64:65], v[64:65], v[168:169]
	v_pk_add_f32 v[58:59], v[58:59], v[170:171]
	v_pk_add_f32 v[60:61], v[60:61], v[172:173]
	v_pk_add_f32 v[54:55], v[54:55], v[174:175]
	v_pk_add_f32 v[56:57], v[56:57], v[176:177]
	v_pk_add_f32 v[50:51], v[50:51], v[178:179]
	v_pk_add_f32 v[52:53], v[52:53], v[180:181]
	v_cvt_pk_bf16_f32 v166, v62, v63
	v_cvt_pk_bf16_f32 v167, v64, v65
	v_cvt_pk_bf16_f32 v168, v58, v59
	v_cvt_pk_bf16_f32 v169, v60, v61
	v_cvt_pk_bf16_f32 v170, v54, v55
	v_cvt_pk_bf16_f32 v171, v56, v57
	v_cvt_pk_bf16_f32 v172, v50, v51
	v_cvt_pk_bf16_f32 v173, v52, v53
	v_mul_f32_e32 v174, v62, v62
	v_mul_f32_e32 v175, v58, v58
	v_mul_f32_e32 v176, v54, v54
	v_mul_f32_e32 v177, v50, v50
	v_fmac_f32_e32 v174, v63, v63
	v_fmac_f32_e32 v175, v59, v59
	v_fmac_f32_e32 v176, v55, v55
	v_fmac_f32_e32 v177, v51, v51
	v_fmac_f32_e32 v174, v64, v64
	v_fmac_f32_e32 v175, v60, v60
	v_fmac_f32_e32 v176, v56, v56
	v_fmac_f32_e32 v177, v52, v52
	v_fmac_f32_e32 v174, v65, v65
	v_fmac_f32_e32 v175, v61, v61
	v_fmac_f32_e32 v176, v57, v57
	v_fmac_f32_e32 v177, v53, v53
	v_add_f32_e32 v174, v174, v175
	v_add_f32_e32 v176, v176, v177
	v_add_f32_e32 v178, v174, v176
	v_mov_b32_e32 v179, v178
	v_permlane16_swap_b32_e32 v166, v168
	v_permlane16_swap_b32_e32 v167, v169
	v_permlane32_swap_b32_e32 v179, v178
	v_permlane16_swap_b32_e32 v170, v172
	v_permlane16_swap_b32_e32 v171, v173
	v_add_u32_e32 v253, 0x40000, v252
	global_store_dwordx4 v253, v[166:169], s[14:15]
	global_store_dwordx4 v253, v[170:173], s[14:15] offset:256
	v_add_f32_e32 v178, v178, v179
	v_mov_b32_e32 v179, v178
	v_add_u32_e32 v189, 0x2000, v189
	s_nop 0
	v_permlane16_swap_b32_e32 v179, v178
	v_add_f32_e32 v178, v178, v179
	s_and_saveexec_b64 s[24:25], s[6:7]
	global_store_dword v189, v178, s[16:17]
	s_or_b64 exec, exec, s[24:25]
	s_waitcnt vmcnt(14)
; __device__ __forceinline__ float bf_lo(unsigned u) { return __uint_as_float(u << 16); }
; __device__ __forceinline__ float bf_hi(unsigned u) { return __uint_as_float(u & 0xffff0000u); }
; __device__ __forceinline__ unsigned pk_bf16(float lo, float hi) { const f32x2 v = {lo, hi}; const bf16x2_t b = __builtin_convertvector(v, bf16x2_t); return __builtin_bit_cast(unsigned, b); }
;     __device__ __forceinline__ void operator()(const f32x4 (&acc)[2][2][4][2], const pg8::Unit& u, int wr, int wc, int fr, int fq) const {
;     ...
;                     for (int bj = 0; bj < 2; ++bj)
; #pragma unroll
;                         for (int n = 0; n < 2; ++n) { const u32x2 w = *(const u32x2*)(XB + off + bj * 128 + n * 16); r4[bj][n] = (f32x4){bf_lo(w.x), bf_hi(w.x), bf_lo(w.y), bf_hi(w.y)}; }
;                 }
; #pragma unroll
;                 for (int bj = 0; bj < 2; ++bj)
; #pragma unroll
;                     for (int n = 0; n < 2; ++n) { const f32x4 x4 = r4[bj][n] + acc[ai][bj][m][n];
;                         q += (x4[0] * x4[0] + x4[1] * x4[1]) + (x4[2] * x4[2] + x4[3] * x4[3]);
;                         u32x2 w; w.x = pk_bf16(x4[0], x4[1]); w.y = pk_bf16(x4[2], x4[3]); *(u32x2*)(XB + off + bj * 128 + n * 16) = w; }
;                 q += __shfl_xor(q, 16); q += __shfl_xor(q, 32);
;                 if (fq == 0) ssq[(size_t)row * 16 + u.pn * 4 + wc] = q;
	v_permlane16_swap_b32_e32 v244, v246
	v_permlane16_swap_b32_e32 v245, v247
	v_permlane16_swap_b32_e32 v248, v250
	v_permlane16_swap_b32_e32 v249, v251
	v_lshlrev_b32_e32 v166, 16, v244
	v_and_b32_e32 v167, 0xffff0000, v244
	v_lshlrev_b32_e32 v168, 16, v245
	v_and_b32_e32 v169, 0xffff0000, v245
	v_lshlrev_b32_e32 v170, 16, v246
	v_and_b32_e32 v171, 0xffff0000, v246
	v_lshlrev_b32_e32 v172, 16, v247
	v_and_b32_e32 v173, 0xffff0000, v247
	v_lshlrev_b32_e32 v174, 16, v248
	v_and_b32_e32 v175, 0xffff0000, v248
	v_lshlrev_b32_e32 v176, 16, v249
	v_and_b32_e32 v177, 0xffff0000, v249
	v_lshlrev_b32_e32 v178, 16, v250
	v_and_b32_e32 v179, 0xffff0000, v250
	v_lshlrev_b32_e32 v180, 16, v251
	v_and_b32_e32 v181, 0xffff0000, v251
	v_pk_add_f32 v[46:47], v[46:47], v[166:167]
	v_pk_add_f32 v[48:49], v[48:49], v[168:169]
	v_pk_add_f32 v[42:43], v[42:43], v[170:171]
	v_pk_add_f32 v[44:45], v[44:45], v[172:173]
	v_pk_add_f32 v[38:39], v[38:39], v[174:175]
	v_pk_add_f32 v[40:41], v[40:41], v[176:177]
	v_pk_add_f32 v[34:35], v[34:35], v[178:179]
	v_pk_add_f32 v[36:37], v[36:37], v[180:181]
	v_cvt_pk_bf16_f32 v166, v46, v47
	v_cvt_pk_bf16_f32 v167, v48, v49
	v_cvt_pk_bf16_f32 v168, v42, v43
	v_cvt_pk_bf16_f32 v169, v44, v45
	v_cvt_pk_bf16_f32 v170, v38, v39
	v_cvt_pk_bf16_f32 v171, v40, v41
	v_cvt_pk_bf16_f32 v172, v34, v35
	v_cvt_pk_bf16_f32 v173, v36, v37
	v_mul_f32_e32 v174, v46, v46
	v_mul_f32_e32 v175, v42, v42
	v_mul_f32_e32 v176, v38, v38
	v_mul_f32_e32 v177, v34, v34
	v_fmac_f32_e32 v174, v47, v47
	v_fmac_f32_e32 v175, v43, v43
	v_fmac_f32_e32 v176, v39, v39
	v_fmac_f32_e32 v177, v35, v35
	v_fmac_f32_e32 v174, v48, v48
	v_fmac_f32_e32 v175, v44, v44
	v_fmac_f32_e32 v176, v40, v40
	v_fmac_f32_e32 v177, v36, v36
	v_fmac_f32_e32 v174, v49, v49
	v_fmac_f32_e32 v175, v45, v45
	v_fmac_f32_e32 v176, v41, v41
	v_fmac_f32_e32 v177, v37, v37
	v_add_f32_e32 v174, v174, v175
	v_add_f32_e32 v176, v176, v177
	v_add_f32_e32 v178, v174, v176
	v_mov_b32_e32 v179, v178
	v_permlane16_swap_b32_e32 v166, v168
	v_permlane16_swap_b32_e32 v167, v169
	v_permlane32_swap_b32_e32 v179, v178
	v_permlane16_swap_b32_e32 v170, v172
	v_permlane16_swap_b32_e32 v171, v173
	v_add_u32_e32 v253, 0x48000, v252
	global_store_dwordx4 v253, v[166:169], s[14:15]
	global_store_dwordx4 v253, v[170:173], s[14:15] offset:256
	v_add_f32_e32 v178, v178, v179
	v_mov_b32_e32 v179, v178
	s_nop 0
	s_nop 0
	v_permlane16_swap_b32_e32 v179, v178
	v_add_f32_e32 v178, v178, v179
	s_and_saveexec_b64 s[24:25], s[6:7]
	global_store_dword v189, v178, s[16:17] offset:1024
	s_or_b64 exec, exec, s[24:25]
	s_waitcnt vmcnt(14)
; __device__ __forceinline__ float bf_lo(unsigned u) { return __uint_as_float(u << 16); }
; __device__ __forceinline__ float bf_hi(unsigned u) { return __uint_as_float(u & 0xffff0000u); }
; __device__ __forceinline__ unsigned pk_bf16(float lo, float hi) { const f32x2 v = {lo, hi}; const bf16x2_t b = __builtin_convertvector(v, bf16x2_t); return __builtin_bit_cast(unsigned, b); }
;     __device__ __forceinline__ void operator()(const f32x4 (&acc)[2][2][4][2], const pg8::Unit& u, int wr, int wc, int fr, int fq) const {
;     ...
;                     for (int bj = 0; bj < 2; ++bj)
; #pragma unroll
;                         for (int n = 0; n < 2; ++n) { const u32x2 w = *(const u32x2*)(XB + off + bj * 128 + n * 16); r4[bj][n] = (f32x4){bf_lo(w.x), bf_hi(w.x), bf_lo(w.y), bf_hi(w.y)}; }
;                 }
; #pragma unroll
;                 for (int bj = 0; bj < 2; ++bj)
; #pragma unroll
;                     for (int n = 0; n < 2; ++n) { const f32x4 x4 = r4[bj][n] + acc[ai][bj][m][n];
;                         q += (x4[0] * x4[0] + x4[1] * x4[1]) + (x4[2] * x4[2] + x4[3] * x4[3]);
;                         u32x2 w; w.x = pk_bf16(x4[0], x4[1]); w.y = pk_bf16(x4[2], x4[3]); *(u32x2*)(XB + off + bj * 128 + n * 16) = w; }
;                 q += __shfl_xor(q, 16); q += __shfl_xor(q, 32);
;                 if (fq == 0) ssq[(size_t)row * 16 + u.pn * 4 + wc] = q;
	v_permlane16_swap_b32_e32 v204, v206
	v_permlane16_swap_b32_e32 v205, v207
	v_permlane16_swap_b32_e32 v208, v210
	v_permlane16_swap_b32_e32 v209, v211
	v_lshlrev_b32_e32 v166, 16, v204
	v_and_b32_e32 v167, 0xffff0000, v204
	v_lshlrev_b32_e32 v168, 16, v205
	v_and_b32_e32 v169, 0xffff0000, v205
	v_lshlrev_b32_e32 v170, 16, v206
	v_and_b32_e32 v171, 0xffff0000, v206
	v_lshlrev_b32_e32 v172, 16, v207
	v_and_b32_e32 v173, 0xffff0000, v207
	v_lshlrev_b32_e32 v174, 16, v208
	v_and_b32_e32 v175, 0xffff0000, v208
	v_lshlrev_b32_e32 v176, 16, v209
	v_and_b32_e32 v177, 0xffff0000, v209
	v_lshlrev_b32_e32 v178, 16, v210
	v_and_b32_e32 v179, 0xffff0000, v210
	v_lshlrev_b32_e32 v180, 16, v211
	v_and_b32_e32 v181, 0xffff0000, v211
	v_pk_add_f32 v[30:31], v[30:31], v[166:167]
	v_pk_add_f32 v[32:33], v[32:33], v[168:169]
	v_pk_add_f32 v[26:27], v[26:27], v[170:171]
	v_pk_add_f32 v[28:29], v[28:29], v[172:173]
	v_pk_add_f32 v[22:23], v[22:23], v[174:175]
	v_pk_add_f32 v[24:25], v[24:25], v[176:177]
	v_pk_add_f32 v[18:19], v[18:19], v[178:179]
	v_pk_add_f32 v[20:21], v[20:21], v[180:181]
	v_cvt_pk_bf16_f32 v166, v30, v31
	v_cvt_pk_bf16_f32 v167, v32, v33
	v_cvt_pk_bf16_f32 v168, v26, v27
	v_cvt_pk_bf16_f32 v169, v28, v29
	v_cvt_pk_bf16_f32 v170, v22, v23
	v_cvt_pk_bf16_f32 v171, v24, v25
	v_cvt_pk_bf16_f32 v172, v18, v19
	v_cvt_pk_bf16_f32 v173, v20, v21
	v_mul_f32_e32 v174, v30, v30
	v_mul_f32_e32 v175, v26, v26
	v_mul_f32_e32 v176, v22, v22
	v_mul_f32_e32 v177, v18, v18
	v_fmac_f32_e32 v174, v31, v31
	v_fmac_f32_e32 v175, v27, v27
	v_fmac_f32_e32 v176, v23, v23
	v_fmac_f32_e32 v177, v19, v19
	v_fmac_f32_e32 v174, v32, v32
	v_fmac_f32_e32 v175, v28, v28
	v_fmac_f32_e32 v176, v24, v24
	v_fmac_f32_e32 v177, v20, v20
	v_fmac_f32_e32 v174, v33, v33
	v_fmac_f32_e32 v175, v29, v29
	v_fmac_f32_e32 v176, v25, v25
	v_fmac_f32_e32 v177, v21, v21
	v_add_f32_e32 v174, v174, v175
	v_add_f32_e32 v176, v176, v177
	v_add_f32_e32 v178, v174, v176
	v_mov_b32_e32 v179, v178
	v_permlane16_swap_b32_e32 v166, v168
	v_permlane16_swap_b32_e32 v167, v169
	v_permlane32_swap_b32_e32 v179, v178
	v_permlane16_swap_b32_e32 v170, v172
	v_permlane16_swap_b32_e32 v171, v173
	v_add_u32_e32 v253, 0x50000, v252
	global_store_dwordx4 v253, v[166:169], s[14:15]
	global_store_dwordx4 v253, v[170:173], s[14:15] offset:256
	v_add_f32_e32 v178, v178, v179
	v_mov_b32_e32 v179, v178
	s_nop 0
	s_nop 0
	v_permlane16_swap_b32_e32 v179, v178
	v_add_f32_e32 v178, v178, v179
	s_and_saveexec_b64 s[24:25], s[6:7]
	global_store_dword v189, v178, s[16:17] offset:2048
	s_or_b64 exec, exec, s[24:25]
	s_waitcnt vmcnt(12)
	v_permlane16_swap_b32_e32 v212, v214
	v_permlane16_swap_b32_e32 v213, v215
	v_permlane16_swap_b32_e32 v216, v218
	v_permlane16_swap_b32_e32 v217, v219
	v_lshlrev_b32_e32 v166, 16, v212
	v_and_b32_e32 v167, 0xffff0000, v212
	v_lshlrev_b32_e32 v168, 16, v213
	v_and_b32_e32 v169, 0xffff0000, v213
	v_lshlrev_b32_e32 v170, 16, v214
	v_and_b32_e32 v171, 0xffff0000, v214
	v_lshlrev_b32_e32 v172, 16, v215
	v_and_b32_e32 v173, 0xffff0000, v215
	v_lshlrev_b32_e32 v174, 16, v216
	v_and_b32_e32 v175, 0xffff0000, v216
	v_lshlrev_b32_e32 v176, 16, v217
	v_and_b32_e32 v177, 0xffff0000, v217
	v_lshlrev_b32_e32 v178, 16, v218
	v_and_b32_e32 v179, 0xffff0000, v218
	v_lshlrev_b32_e32 v180, 16, v219
	v_and_b32_e32 v181, 0xffff0000, v219
	v_pk_add_f32 v[14:15], v[14:15], v[166:167]
	v_pk_add_f32 v[16:17], v[16:17], v[168:169]
	v_pk_add_f32 v[10:11], v[10:11], v[170:171]
	v_pk_add_f32 v[12:13], v[12:13], v[172:173]
	v_pk_add_f32 v[6:7], v[6:7], v[174:175]
	v_pk_add_f32 v[8:9], v[8:9], v[176:177]
	v_pk_add_f32 v[2:3], v[2:3], v[178:179]
	v_pk_add_f32 v[4:5], v[4:5], v[180:181]
	v_cvt_pk_bf16_f32 v166, v14, v15
	v_cvt_pk_bf16_f32 v167, v16, v17
	v_cvt_pk_bf16_f32 v168, v10, v11
	v_cvt_pk_bf16_f32 v169, v12, v13
	v_cvt_pk_bf16_f32 v170, v6, v7
	v_cvt_pk_bf16_f32 v171, v8, v9
	v_cvt_pk_bf16_f32 v172, v2, v3
	v_cvt_pk_bf16_f32 v173, v4, v5
	v_mul_f32_e32 v174, v14, v14
	v_mul_f32_e32 v175, v10, v10
	v_mul_f32_e32 v176, v6, v6
	v_mul_f32_e32 v177, v2, v2
	v_fmac_f32_e32 v174, v15, v15
	v_fmac_f32_e32 v175, v11, v11
	v_fmac_f32_e32 v176, v7, v7
	v_fmac_f32_e32 v177, v3, v3
	v_fmac_f32_e32 v174, v16, v16
	v_fmac_f32_e32 v175, v12, v12
	v_fmac_f32_e32 v176, v8, v8
	v_fmac_f32_e32 v177, v4, v4
	v_fmac_f32_e32 v174, v17, v17
	v_fmac_f32_e32 v175, v13, v13
	v_fmac_f32_e32 v176, v9, v9
	v_fmac_f32_e32 v177, v5, v5
	v_add_f32_e32 v174, v174, v175
	v_add_f32_e32 v176, v176, v177
	v_add_f32_e32 v178, v174, v176
	v_mov_b32_e32 v179, v178
	v_permlane16_swap_b32_e32 v166, v168
	v_permlane16_swap_b32_e32 v167, v169
	v_permlane32_swap_b32_e32 v179, v178
	v_permlane16_swap_b32_e32 v170, v172
	v_permlane16_swap_b32_e32 v171, v173
	v_add_u32_e32 v253, 0x58000, v252
	global_store_dwordx4 v253, v[166:169], s[14:15]
	global_store_dwordx4 v253, v[170:173], s[14:15] offset:256
	v_add_f32_e32 v178, v178, v179
	v_mov_b32_e32 v179, v178
	s_nop 0
	s_nop 0
	v_permlane16_swap_b32_e32 v179, v178
	v_add_f32_e32 v178, v178, v179
	s_and_saveexec_b64 s[24:25], s[6:7]
	global_store_dword v189, v178, s[16:17] offset:3072
	s_or_b64 exec, exec, s[24:25]
